# v40: + ODIN epilogue row-stat loads issued three pieces ahead (rotating register sets, counted waits)
# baseline (speedup 1.0000x reference)
.LBB0_1239:
	s_lshl_b32 s33, s33, 8
	s_add_i32 s33, s33, s36
	v_or_b32_e32 v156, s33, v160
	v_ashrrev_i32_e32 v157, 31, v156
	v_lshlrev_b64 v[158:159], 6, v[156:157]
	v_lshl_add_u64 v[158:159], s[72:73], 0, v[158:159]
	global_load_dwordx4 v[164:167], v[158:159], off offset:48
	global_load_dwordx4 v[168:171], v[158:159], off offset:32
	global_load_dwordx4 v[174:177], v[158:159], off offset:16
	global_load_dwordx4 v[178:181], v[158:159], off
	v_mov_b32_e32 v246, v158
	v_mov_b32_e32 v247, v159
	v_add_co_u32_e32 v248, vcc, 0x2000, v158
	s_nop 1
	v_addc_co_u32_e32 v249, vcc, 0, v159, vcc
	global_load_dwordx4 v[198:201], v[246:247], off offset:1072
	global_load_dwordx4 v[202:205], v[246:247], off offset:1056
	global_load_dwordx4 v[206:209], v[246:247], off offset:1040
	global_load_dwordx4 v[210:213], v[246:247], off offset:1024
	global_load_dwordx4 v[214:217], v[246:247], off offset:2096
	global_load_dwordx4 v[218:221], v[246:247], off offset:2080
	global_load_dwordx4 v[222:225], v[246:247], off offset:2064
	global_load_dwordx4 v[226:229], v[246:247], off offset:2048
	global_load_dwordx4 v[230:233], v[246:247], off offset:3120
	global_load_dwordx4 v[234:237], v[246:247], off offset:3104
	global_load_dwordx4 v[238:241], v[246:247], off offset:3088
	global_load_dwordx4 v[242:245], v[246:247], off offset:3072
	v_add_co_u32_e32 v196, vcc, 0x2000, v158
	s_nop 1
	v_addc_co_u32_e32 v197, vcc, 0, v159, vcc
	v_lshl_or_b32 v154, s44, 8, v162
	s_cmp_gt_i32 s44, 1
	s_cselect_b64 s[0:1], -1, 0
	s_ashr_i32 s44, s33, 4
	s_addk_i32 s44, 0x8000
	s_mov_b64 s[4:5], -1
	s_waitcnt vmcnt(12)
	v_add_f32_e32 v168, v168, v169
	v_add_f32_e32 v170, v170, v171
	v_mov_b32_e32 v158, v179
	v_mov_b32_e32 v159, v180
	v_mov_b32_e32 v179, v181
	v_pk_add_f32 v[158:159], v[158:159], v[178:179]
	v_mov_b32_e32 v178, v175
	v_mov_b32_e32 v179, v176
	v_mov_b32_e32 v175, v177
	v_pk_add_f32 v[174:175], v[178:179], v[174:175]
	v_pk_add_f32 v[158:159], v[158:159], v[158:159] op_sel:[0,1] op_sel_hi:[1,0]
	v_pk_add_f32 v[174:175], v[174:175], v[174:175] op_sel:[0,1] op_sel_hi:[1,0]
	v_mov_b32_e32 v159, v164
	v_mov_b32_e32 v175, v165
	v_mov_b32_e32 v169, v166
	v_mov_b32_e32 v171, v167
	v_pk_add_f32 v[158:159], v[158:159], v[174:175]
	v_pk_add_f32 v[164:165], v[168:169], v[170:171]
	s_nop 0
	v_pk_add_f32 v[158:159], v[158:159], v[164:165]
	s_nop 0
	v_add_f32_e32 v155, v158, v159
	v_fmamk_f32 v155, v155, 0x3a800000, v184
	v_cmp_gt_f32_e32 vcc, s80, v155
	v_mul_f32_e32 v158, 0x4b800000, v155
	s_nop 0
	v_cndmask_b32_e32 v155, v155, v158, vcc
	v_rsq_f32_e32 v155, v155
	s_nop 0
	v_mul_f32_e32 v158, 0x45800000, v155
	v_cndmask_b32_e32 v158, v155, v158, vcc
	v_pk_mul_f32 v[122:123], v[122:123], v[158:159] op_sel_hi:[1,0]
	v_pk_mul_f32 v[126:127], v[126:127], v[158:159] op_sel_hi:[1,0]
	v_pk_mul_f32 v[124:125], v[124:125], v[158:159] op_sel_hi:[1,0]
	v_pk_mul_f32 v[128:129], v[128:129], v[158:159] op_sel_hi:[1,0]
	v_lshlrev_b32_e32 v155, 6, v154
	s_and_b64 vcc, exec, s[0:1]
	v_and_b32_e32 v164, 0xffffdc00, v155
	v_cvt_pk_bf16_f32 v122, v122, v123
	v_cvt_pk_bf16_f32 v123, v124, v125
	v_cvt_pk_bf16_f32 v124, v126, v127
	v_cvt_pk_bf16_f32 v125, v128, v129
	s_cbranch_vccz .LBB0_1241
	v_add_u32_e32 v126, s44, v164
	v_ashrrev_i32_e32 v127, 31, v126
	v_lshlrev_b64 v[126:127], 9, v[126:127]
	v_lshl_add_u64 v[126:127], v[148:149], 0, v[126:127]
	global_store_dwordx4 v[126:127], v[122:125], off
	s_mov_b64 s[4:5], 0

.LBB0_1247:
	s_or_b32 s0, s33, 16
	s_nop 0
	v_or_b32_e32 v114, s0, v160
	v_ashrrev_i32_e32 v115, 31, v114
	v_lshlrev_b64 v[116:117], 6, v[114:115]
	v_lshl_add_u64 v[120:121], s[72:73], 0, v[116:117]
	s_ashr_i32 s24, s0, 4
	s_addk_i32 s24, 0x8000
	s_mov_b64 s[0:1], -1
	s_waitcnt vmcnt(10)
	v_mov_b32_e32 v116, v198
	v_mov_b32_e32 v117, v199
	v_mov_b32_e32 v118, v200
	v_mov_b32_e32 v119, v201
	v_mov_b32_e32 v124, v202
	v_mov_b32_e32 v125, v203
	v_mov_b32_e32 v126, v204
	v_mov_b32_e32 v127, v205
	v_mov_b32_e32 v156, v206
	v_mov_b32_e32 v157, v207
	v_mov_b32_e32 v158, v208
	v_mov_b32_e32 v159, v209
	v_mov_b32_e32 v166, v210
	v_mov_b32_e32 v167, v211
	v_mov_b32_e32 v168, v212
	v_mov_b32_e32 v169, v213
	global_load_dwordx4 v[198:201], v[248:249], off offset:48
	global_load_dwordx4 v[202:205], v[248:249], off offset:32
	global_load_dwordx4 v[206:209], v[248:249], off offset:16
	global_load_dwordx4 v[210:213], v[248:249], off
	v_add_f32_e32 v124, v124, v125
	v_mov_b32_e32 v128, v157
	v_mov_b32_e32 v120, v167
	v_mov_b32_e32 v121, v168
	v_mov_b32_e32 v167, v169
	v_mov_b32_e32 v129, v158
	v_mov_b32_e32 v157, v159
	v_pk_add_f32 v[120:121], v[120:121], v[166:167]
	v_pk_add_f32 v[128:129], v[128:129], v[156:157]
	v_pk_add_f32 v[120:121], v[120:121], v[120:121] op_sel:[0,1] op_sel_hi:[1,0]
	v_pk_add_f32 v[128:129], v[128:129], v[128:129] op_sel:[0,1] op_sel_hi:[1,0]
	v_add_f32_e32 v126, v126, v127
	v_mov_b32_e32 v121, v116
	v_mov_b32_e32 v129, v117
	v_mov_b32_e32 v125, v118
	v_mov_b32_e32 v127, v119
	v_pk_add_f32 v[116:117], v[120:121], v[128:129]
	v_pk_add_f32 v[118:119], v[124:125], v[126:127]
	s_nop 0
	v_pk_add_f32 v[116:117], v[116:117], v[118:119]
	s_nop 0
	v_add_f32_e32 v116, v116, v117
	v_fmamk_f32 v116, v116, 0x3a800000, v184
	v_cmp_gt_f32_e32 vcc, s80, v116
	v_mul_f32_e32 v117, 0x4b800000, v116
	s_nop 0
	v_cndmask_b32_e32 v116, v116, v117, vcc
	v_rsq_f32_e32 v116, v116
	s_nop 0
	v_mul_f32_e32 v117, 0x45800000, v116
	v_cndmask_b32_e32 v116, v116, v117, vcc
	v_pk_mul_f32 v[118:119], v[110:111], v[116:117] op_sel_hi:[1,0]
	v_pk_mul_f32 v[110:111], v[106:107], v[116:117] op_sel_hi:[1,0]
	v_pk_mul_f32 v[120:121], v[112:113], v[116:117] op_sel_hi:[1,0]
	v_pk_mul_f32 v[112:113], v[108:109], v[116:117] op_sel_hi:[1,0]
	s_and_b64 vcc, exec, s[4:5]
	v_cvt_pk_bf16_f32 v106, v118, v119
	v_cvt_pk_bf16_f32 v107, v120, v121
	v_cvt_pk_bf16_f32 v108, v110, v111
	v_cvt_pk_bf16_f32 v109, v112, v113
	s_cbranch_vccnz .LBB0_1249
	v_add_u32_e32 v110, s24, v164
	v_ashrrev_i32_e32 v111, 31, v110
	v_lshlrev_b64 v[110:111], 9, v[110:111]
	v_lshl_add_u64 v[110:111], v[148:149], 0, v[110:111]
	s_mov_b64 s[0:1], 0
	global_store_dwordx4 v[110:111], v[106:109], off

.LBB0_1255:
	s_or_b32 s0, s33, 32
	s_nop 0
	v_or_b32_e32 v98, s0, v160
	v_ashrrev_i32_e32 v99, 31, v98
	v_lshlrev_b64 v[100:101], 6, v[98:99]
	v_lshl_add_u64 v[112:113], s[72:73], 0, v[100:101]
	s_ashr_i32 s24, s0, 4
	s_addk_i32 s24, 0x8000
	s_mov_b64 s[0:1], -1
	s_waitcnt vmcnt(12)
	v_mov_b32_e32 v100, v214
	v_mov_b32_e32 v101, v215
	v_mov_b32_e32 v102, v216
	v_mov_b32_e32 v103, v217
	v_mov_b32_e32 v104, v218
	v_mov_b32_e32 v105, v219
	v_mov_b32_e32 v106, v220
	v_mov_b32_e32 v107, v221
	v_mov_b32_e32 v108, v222
	v_mov_b32_e32 v109, v223
	v_mov_b32_e32 v110, v224
	v_mov_b32_e32 v111, v225
	v_mov_b32_e32 v112, v226
	v_mov_b32_e32 v113, v227
	v_mov_b32_e32 v114, v228
	v_mov_b32_e32 v115, v229
	global_load_dwordx4 v[214:217], v[248:249], off offset:1072
	global_load_dwordx4 v[218:221], v[248:249], off offset:1056
	global_load_dwordx4 v[222:225], v[248:249], off offset:1040
	global_load_dwordx4 v[226:229], v[248:249], off offset:1024
	v_add_f32_e32 v104, v104, v105
	v_add_f32_e32 v106, v106, v107
	v_mov_b32_e32 v116, v113
	v_mov_b32_e32 v117, v114
	v_mov_b32_e32 v113, v115
	v_mov_b32_e32 v114, v109
	v_mov_b32_e32 v115, v110
	v_mov_b32_e32 v109, v111
	v_pk_add_f32 v[112:113], v[116:117], v[112:113]
	v_pk_add_f32 v[108:109], v[114:115], v[108:109]
	v_pk_add_f32 v[112:113], v[112:113], v[112:113] op_sel:[0,1] op_sel_hi:[1,0]
	v_pk_add_f32 v[108:109], v[108:109], v[108:109] op_sel:[0,1] op_sel_hi:[1,0]
	v_mov_b32_e32 v113, v100
	v_mov_b32_e32 v109, v101
	v_mov_b32_e32 v105, v102
	v_mov_b32_e32 v107, v103
	v_pk_add_f32 v[100:101], v[112:113], v[108:109]
	v_pk_add_f32 v[102:103], v[104:105], v[106:107]
	s_nop 0
	v_pk_add_f32 v[100:101], v[100:101], v[102:103]
	s_nop 0
	v_add_f32_e32 v100, v100, v101
	v_fmamk_f32 v100, v100, 0x3a800000, v184
	v_cmp_gt_f32_e32 vcc, s80, v100
	v_mul_f32_e32 v101, 0x4b800000, v100
	s_nop 0
	v_cndmask_b32_e32 v100, v100, v101, vcc
	v_rsq_f32_e32 v100, v100
	s_nop 0
	v_mul_f32_e32 v101, 0x45800000, v100
	v_cndmask_b32_e32 v100, v100, v101, vcc
	v_pk_mul_f32 v[102:103], v[94:95], v[100:101] op_sel_hi:[1,0]
	v_pk_mul_f32 v[94:95], v[90:91], v[100:101] op_sel_hi:[1,0]
	v_pk_mul_f32 v[104:105], v[96:97], v[100:101] op_sel_hi:[1,0]
	v_pk_mul_f32 v[96:97], v[92:93], v[100:101] op_sel_hi:[1,0]
	s_and_b64 vcc, exec, s[4:5]
	v_cvt_pk_bf16_f32 v90, v102, v103
	v_cvt_pk_bf16_f32 v91, v104, v105
	v_cvt_pk_bf16_f32 v92, v94, v95
	v_cvt_pk_bf16_f32 v93, v96, v97
	s_cbranch_vccnz .LBB0_1257
	v_add_u32_e32 v94, s24, v164
	v_ashrrev_i32_e32 v95, 31, v94
	v_lshlrev_b64 v[94:95], 9, v[94:95]
	v_lshl_add_u64 v[94:95], v[148:149], 0, v[94:95]
	s_mov_b64 s[0:1], 0
	global_store_dwordx4 v[94:95], v[90:93], off

.LBB0_1263:
	s_or_b32 s0, s33, 48
	s_nop 0
	v_or_b32_e32 v82, s0, v160
	v_ashrrev_i32_e32 v83, 31, v82
	v_lshlrev_b64 v[84:85], 6, v[82:83]
	v_lshl_add_u64 v[96:97], s[72:73], 0, v[84:85]
	s_ashr_i32 s24, s0, 4
	s_addk_i32 s24, 0x8000
	s_mov_b64 s[0:1], -1
	s_waitcnt vmcnt(14)
	v_mov_b32_e32 v84, v230
	v_mov_b32_e32 v85, v231
	v_mov_b32_e32 v86, v232
	v_mov_b32_e32 v87, v233
	v_mov_b32_e32 v88, v234
	v_mov_b32_e32 v89, v235
	v_mov_b32_e32 v90, v236
	v_mov_b32_e32 v91, v237
	v_mov_b32_e32 v92, v238
	v_mov_b32_e32 v93, v239
	v_mov_b32_e32 v94, v240
	v_mov_b32_e32 v95, v241
	v_mov_b32_e32 v96, v242
	v_mov_b32_e32 v97, v243
	v_mov_b32_e32 v98, v244
	v_mov_b32_e32 v99, v245
	global_load_dwordx4 v[230:233], v[248:249], off offset:2096
	global_load_dwordx4 v[234:237], v[248:249], off offset:2080
	global_load_dwordx4 v[238:241], v[248:249], off offset:2064
	global_load_dwordx4 v[242:245], v[248:249], off offset:2048
	v_add_f32_e32 v88, v88, v89
	v_add_f32_e32 v90, v90, v91
	v_mov_b32_e32 v100, v97
	v_mov_b32_e32 v101, v98
	v_mov_b32_e32 v97, v99
	v_mov_b32_e32 v98, v93
	v_mov_b32_e32 v99, v94
	v_mov_b32_e32 v93, v95
	v_pk_add_f32 v[96:97], v[100:101], v[96:97]
	v_pk_add_f32 v[92:93], v[98:99], v[92:93]
	v_pk_add_f32 v[96:97], v[96:97], v[96:97] op_sel:[0,1] op_sel_hi:[1,0]
	v_pk_add_f32 v[92:93], v[92:93], v[92:93] op_sel:[0,1] op_sel_hi:[1,0]
	v_mov_b32_e32 v97, v84
	v_mov_b32_e32 v93, v85
	v_mov_b32_e32 v89, v86
	v_mov_b32_e32 v91, v87
	v_pk_add_f32 v[84:85], v[96:97], v[92:93]
	v_pk_add_f32 v[86:87], v[88:89], v[90:91]
	s_nop 0
	v_pk_add_f32 v[84:85], v[84:85], v[86:87]
	s_nop 0
	v_add_f32_e32 v84, v84, v85
	v_fmamk_f32 v84, v84, 0x3a800000, v184
	v_cmp_gt_f32_e32 vcc, s80, v84
	v_mul_f32_e32 v85, 0x4b800000, v84
	s_nop 0
	v_cndmask_b32_e32 v84, v84, v85, vcc
	v_rsq_f32_e32 v84, v84
	s_nop 0
	v_mul_f32_e32 v85, 0x45800000, v84
	v_cndmask_b32_e32 v84, v84, v85, vcc
	v_pk_mul_f32 v[86:87], v[78:79], v[84:85] op_sel_hi:[1,0]
	v_pk_mul_f32 v[78:79], v[74:75], v[84:85] op_sel_hi:[1,0]
	v_pk_mul_f32 v[88:89], v[80:81], v[84:85] op_sel_hi:[1,0]
	v_pk_mul_f32 v[80:81], v[76:77], v[84:85] op_sel_hi:[1,0]
	s_and_b64 vcc, exec, s[4:5]
	v_cvt_pk_bf16_f32 v74, v86, v87
	v_cvt_pk_bf16_f32 v75, v88, v89
	v_cvt_pk_bf16_f32 v76, v78, v79
	v_cvt_pk_bf16_f32 v77, v80, v81
	s_cbranch_vccnz .LBB0_1265
	v_add_u32_e32 v78, s24, v164
	v_ashrrev_i32_e32 v79, 31, v78
	v_lshlrev_b64 v[78:79], 9, v[78:79]
	v_lshl_add_u64 v[78:79], v[148:149], 0, v[78:79]
	s_mov_b64 s[0:1], 0
	global_store_dwordx4 v[78:79], v[74:77], off

.LBB0_1271:
	s_add_i32 s0, s33, 0x80
	s_nop 0
	v_or_b32_e32 v66, s0, v160
	v_ashrrev_i32_e32 v67, 31, v66
	v_lshlrev_b64 v[68:69], 6, v[66:67]
	v_lshl_add_u64 v[80:81], s[72:73], 0, v[68:69]
	s_ashr_i32 s24, s0, 4
	s_addk_i32 s24, 0x8000
	s_mov_b64 s[0:1], -1
	s_waitcnt vmcnt(14)
	v_mov_b32_e32 v68, v198
	v_mov_b32_e32 v69, v199
	v_mov_b32_e32 v70, v200
	v_mov_b32_e32 v71, v201
	v_mov_b32_e32 v72, v202
	v_mov_b32_e32 v73, v203
	v_mov_b32_e32 v74, v204
	v_mov_b32_e32 v75, v205
	v_mov_b32_e32 v76, v206
	v_mov_b32_e32 v77, v207
	v_mov_b32_e32 v78, v208
	v_mov_b32_e32 v79, v209
	v_mov_b32_e32 v80, v210
	v_mov_b32_e32 v81, v211
	v_mov_b32_e32 v82, v212
	v_mov_b32_e32 v83, v213
	global_load_dwordx4 v[198:201], v[248:249], off offset:3120
	global_load_dwordx4 v[202:205], v[248:249], off offset:3104
	global_load_dwordx4 v[206:209], v[248:249], off offset:3088
	global_load_dwordx4 v[210:213], v[248:249], off offset:3072
	v_add_f32_e32 v72, v72, v73
	v_add_f32_e32 v74, v74, v75
	v_mov_b32_e32 v84, v81
	v_mov_b32_e32 v85, v82
	v_mov_b32_e32 v81, v83
	v_mov_b32_e32 v82, v77
	v_mov_b32_e32 v83, v78
	v_mov_b32_e32 v77, v79
	v_pk_add_f32 v[80:81], v[84:85], v[80:81]
	v_pk_add_f32 v[76:77], v[82:83], v[76:77]
	v_pk_add_f32 v[80:81], v[80:81], v[80:81] op_sel:[0,1] op_sel_hi:[1,0]
	v_pk_add_f32 v[76:77], v[76:77], v[76:77] op_sel:[0,1] op_sel_hi:[1,0]
	v_mov_b32_e32 v81, v68
	v_mov_b32_e32 v77, v69
	v_mov_b32_e32 v73, v70
	v_mov_b32_e32 v75, v71
	v_pk_add_f32 v[68:69], v[80:81], v[76:77]
	v_pk_add_f32 v[70:71], v[72:73], v[74:75]
	s_nop 0
	v_pk_add_f32 v[68:69], v[68:69], v[70:71]
	s_nop 0
	v_add_f32_e32 v68, v68, v69
	v_fmamk_f32 v68, v68, 0x3a800000, v184
	v_cmp_gt_f32_e32 vcc, s80, v68
	v_mul_f32_e32 v69, 0x4b800000, v68
	s_nop 0
	v_cndmask_b32_e32 v68, v68, v69, vcc
	v_rsq_f32_e32 v68, v68
	s_nop 0
	v_mul_f32_e32 v69, 0x45800000, v68
	v_cndmask_b32_e32 v68, v68, v69, vcc
	v_pk_mul_f32 v[70:71], v[62:63], v[68:69] op_sel_hi:[1,0]
	v_pk_mul_f32 v[62:63], v[58:59], v[68:69] op_sel_hi:[1,0]
	v_pk_mul_f32 v[72:73], v[64:65], v[68:69] op_sel_hi:[1,0]
	v_pk_mul_f32 v[64:65], v[60:61], v[68:69] op_sel_hi:[1,0]
	s_and_b64 vcc, exec, s[4:5]
	v_cvt_pk_bf16_f32 v58, v70, v71
	v_cvt_pk_bf16_f32 v59, v72, v73
	v_cvt_pk_bf16_f32 v60, v62, v63
	v_cvt_pk_bf16_f32 v61, v64, v65
	s_cbranch_vccnz .LBB0_1273
	v_add_u32_e32 v62, s24, v164
	v_ashrrev_i32_e32 v63, 31, v62
	v_lshlrev_b64 v[62:63], 9, v[62:63]
	v_lshl_add_u64 v[62:63], v[148:149], 0, v[62:63]
	s_mov_b64 s[0:1], 0
	global_store_dwordx4 v[62:63], v[58:61], off

.LBB0_1279:
	s_add_i32 s0, s33, 0x90
	s_nop 0
	v_or_b32_e32 v50, s0, v160
	v_ashrrev_i32_e32 v51, 31, v50
	v_lshlrev_b64 v[52:53], 6, v[50:51]
	v_lshl_add_u64 v[64:65], s[72:73], 0, v[52:53]
	s_ashr_i32 s24, s0, 4
	s_addk_i32 s24, 0x8000
	s_mov_b64 s[0:1], -1
	s_waitcnt vmcnt(14)
	v_mov_b32_e32 v52, v214
	v_mov_b32_e32 v53, v215
	v_mov_b32_e32 v54, v216
	v_mov_b32_e32 v55, v217
	v_mov_b32_e32 v56, v218
	v_mov_b32_e32 v57, v219
	v_mov_b32_e32 v58, v220
	v_mov_b32_e32 v59, v221
	v_mov_b32_e32 v60, v222
	v_mov_b32_e32 v61, v223
	v_mov_b32_e32 v62, v224
	v_mov_b32_e32 v63, v225
	v_mov_b32_e32 v64, v226
	v_mov_b32_e32 v65, v227
	v_mov_b32_e32 v66, v228
	v_mov_b32_e32 v67, v229
	v_add_f32_e32 v56, v56, v57
	v_add_f32_e32 v58, v58, v59
	v_mov_b32_e32 v68, v65
	v_mov_b32_e32 v69, v66
	v_mov_b32_e32 v65, v67
	v_mov_b32_e32 v66, v61
	v_mov_b32_e32 v67, v62
	v_mov_b32_e32 v61, v63
	v_pk_add_f32 v[64:65], v[68:69], v[64:65]
	v_pk_add_f32 v[60:61], v[66:67], v[60:61]
	v_pk_add_f32 v[64:65], v[64:65], v[64:65] op_sel:[0,1] op_sel_hi:[1,0]
	v_pk_add_f32 v[60:61], v[60:61], v[60:61] op_sel:[0,1] op_sel_hi:[1,0]
	v_mov_b32_e32 v65, v52
	v_mov_b32_e32 v61, v53
	v_mov_b32_e32 v57, v54
	v_mov_b32_e32 v59, v55
	v_pk_add_f32 v[52:53], v[64:65], v[60:61]
	v_pk_add_f32 v[54:55], v[56:57], v[58:59]
	s_nop 0
	v_pk_add_f32 v[52:53], v[52:53], v[54:55]
	s_nop 0
	v_add_f32_e32 v52, v52, v53
	v_fmamk_f32 v52, v52, 0x3a800000, v184
	v_cmp_gt_f32_e32 vcc, s80, v52
	v_mul_f32_e32 v53, 0x4b800000, v52
	s_nop 0
	v_cndmask_b32_e32 v52, v52, v53, vcc
	v_rsq_f32_e32 v52, v52
	s_nop 0
	v_mul_f32_e32 v53, 0x45800000, v52
	v_cndmask_b32_e32 v52, v52, v53, vcc
	v_pk_mul_f32 v[54:55], v[46:47], v[52:53] op_sel_hi:[1,0]
	v_pk_mul_f32 v[46:47], v[42:43], v[52:53] op_sel_hi:[1,0]
	v_pk_mul_f32 v[56:57], v[48:49], v[52:53] op_sel_hi:[1,0]
	v_pk_mul_f32 v[48:49], v[44:45], v[52:53] op_sel_hi:[1,0]
	s_and_b64 vcc, exec, s[4:5]
	v_cvt_pk_bf16_f32 v42, v54, v55
	v_cvt_pk_bf16_f32 v43, v56, v57
	v_cvt_pk_bf16_f32 v44, v46, v47
	v_cvt_pk_bf16_f32 v45, v48, v49
	s_cbranch_vccnz .LBB0_1281
	v_add_u32_e32 v46, s24, v164
	v_ashrrev_i32_e32 v47, 31, v46
	v_lshlrev_b64 v[46:47], 9, v[46:47]
	v_lshl_add_u64 v[46:47], v[148:149], 0, v[46:47]
	s_mov_b64 s[0:1], 0
	global_store_dwordx4 v[46:47], v[42:45], off

.LBB0_1287:
	s_add_i32 s0, s33, 0xa0
	s_nop 0
	v_or_b32_e32 v34, s0, v160
	v_ashrrev_i32_e32 v35, 31, v34
	v_lshlrev_b64 v[36:37], 6, v[34:35]
	v_lshl_add_u64 v[48:49], s[72:73], 0, v[36:37]
	s_ashr_i32 s24, s0, 4
	s_addk_i32 s24, 0x8000
	s_mov_b64 s[0:1], -1
	s_waitcnt vmcnt(10)
	v_mov_b32_e32 v36, v230
	v_mov_b32_e32 v37, v231
	v_mov_b32_e32 v38, v232
	v_mov_b32_e32 v39, v233
	v_mov_b32_e32 v40, v234
	v_mov_b32_e32 v41, v235
	v_mov_b32_e32 v42, v236
	v_mov_b32_e32 v43, v237
	v_mov_b32_e32 v44, v238
	v_mov_b32_e32 v45, v239
	v_mov_b32_e32 v46, v240
	v_mov_b32_e32 v47, v241
	v_mov_b32_e32 v48, v242
	v_mov_b32_e32 v49, v243
	v_mov_b32_e32 v50, v244
	v_mov_b32_e32 v51, v245
	v_add_f32_e32 v40, v40, v41
	v_add_f32_e32 v42, v42, v43
	v_mov_b32_e32 v52, v49
	v_mov_b32_e32 v53, v50
	v_mov_b32_e32 v49, v51
	v_mov_b32_e32 v50, v45
	v_mov_b32_e32 v51, v46
	v_mov_b32_e32 v45, v47
	v_pk_add_f32 v[48:49], v[52:53], v[48:49]
	v_pk_add_f32 v[44:45], v[50:51], v[44:45]
	v_pk_add_f32 v[48:49], v[48:49], v[48:49] op_sel:[0,1] op_sel_hi:[1,0]
	v_pk_add_f32 v[44:45], v[44:45], v[44:45] op_sel:[0,1] op_sel_hi:[1,0]
	v_mov_b32_e32 v49, v36
	v_mov_b32_e32 v45, v37
	v_mov_b32_e32 v41, v38
	v_mov_b32_e32 v43, v39
	v_pk_add_f32 v[36:37], v[48:49], v[44:45]
	v_pk_add_f32 v[38:39], v[40:41], v[42:43]
	s_nop 0
	v_pk_add_f32 v[36:37], v[36:37], v[38:39]
	s_nop 0
	v_add_f32_e32 v36, v36, v37
	v_fmamk_f32 v36, v36, 0x3a800000, v184
	v_cmp_gt_f32_e32 vcc, s80, v36
	v_mul_f32_e32 v37, 0x4b800000, v36
	s_nop 0
	v_cndmask_b32_e32 v36, v36, v37, vcc
	v_rsq_f32_e32 v36, v36
	s_nop 0
	v_mul_f32_e32 v37, 0x45800000, v36
	v_cndmask_b32_e32 v36, v36, v37, vcc
	v_pk_mul_f32 v[38:39], v[30:31], v[36:37] op_sel_hi:[1,0]
	v_pk_mul_f32 v[30:31], v[26:27], v[36:37] op_sel_hi:[1,0]
	v_pk_mul_f32 v[40:41], v[32:33], v[36:37] op_sel_hi:[1,0]
	v_pk_mul_f32 v[32:33], v[28:29], v[36:37] op_sel_hi:[1,0]
	s_and_b64 vcc, exec, s[4:5]
	v_cvt_pk_bf16_f32 v26, v38, v39
	v_cvt_pk_bf16_f32 v27, v40, v41
	v_cvt_pk_bf16_f32 v28, v30, v31
	v_cvt_pk_bf16_f32 v29, v32, v33
	s_cbranch_vccnz .LBB0_1289
	v_add_u32_e32 v30, s24, v164
	v_ashrrev_i32_e32 v31, 31, v30
	v_lshlrev_b64 v[30:31], 9, v[30:31]
	v_lshl_add_u64 v[30:31], v[148:149], 0, v[30:31]
	s_mov_b64 s[0:1], 0
	global_store_dwordx4 v[30:31], v[26:29], off

.LBB0_1295:
	s_addk_i32 s33, 0xb0
	s_nop 0
	v_or_b32_e32 v18, s33, v160
	v_ashrrev_i32_e32 v19, 31, v18
	v_lshlrev_b64 v[20:21], 6, v[18:19]
	v_lshl_add_u64 v[32:33], s[72:73], 0, v[20:21]
	s_ashr_i32 s24, s33, 4
	s_addk_i32 s24, 0x8000
	s_mov_b64 s[0:1], -1
	s_waitcnt vmcnt(6)
	v_mov_b32_e32 v20, v198
	v_mov_b32_e32 v21, v199
	v_mov_b32_e32 v22, v200
	v_mov_b32_e32 v23, v201
	v_mov_b32_e32 v24, v202
	v_mov_b32_e32 v25, v203
	v_mov_b32_e32 v26, v204
	v_mov_b32_e32 v27, v205
	v_mov_b32_e32 v28, v206
	v_mov_b32_e32 v29, v207
	v_mov_b32_e32 v30, v208
	v_mov_b32_e32 v31, v209
	v_mov_b32_e32 v32, v210
	v_mov_b32_e32 v33, v211
	v_mov_b32_e32 v34, v212
	v_mov_b32_e32 v35, v213
	v_add_f32_e32 v24, v24, v25
	v_add_f32_e32 v26, v26, v27
	v_mov_b32_e32 v36, v33
	v_mov_b32_e32 v37, v34
	v_mov_b32_e32 v33, v35
	v_mov_b32_e32 v34, v29
	v_mov_b32_e32 v35, v30
	v_mov_b32_e32 v29, v31
	v_pk_add_f32 v[32:33], v[36:37], v[32:33]
	v_pk_add_f32 v[28:29], v[34:35], v[28:29]
	v_pk_add_f32 v[32:33], v[32:33], v[32:33] op_sel:[0,1] op_sel_hi:[1,0]
	v_pk_add_f32 v[28:29], v[28:29], v[28:29] op_sel:[0,1] op_sel_hi:[1,0]
	v_mov_b32_e32 v33, v20
	v_mov_b32_e32 v29, v21
	v_mov_b32_e32 v25, v22
	v_mov_b32_e32 v27, v23
	v_pk_add_f32 v[20:21], v[32:33], v[28:29]
	v_pk_add_f32 v[22:23], v[24:25], v[26:27]
	s_nop 0
	v_pk_add_f32 v[20:21], v[20:21], v[22:23]
	s_nop 0
	v_add_f32_e32 v20, v20, v21
	v_fmamk_f32 v20, v20, 0x3a800000, v184
	v_cmp_gt_f32_e32 vcc, s80, v20
	v_mul_f32_e32 v21, 0x4b800000, v20
	s_nop 0
	v_cndmask_b32_e32 v20, v20, v21, vcc
	v_rsq_f32_e32 v20, v20
	s_nop 0
	v_mul_f32_e32 v21, 0x45800000, v20
	v_cndmask_b32_e32 v20, v20, v21, vcc
	v_pk_mul_f32 v[22:23], v[14:15], v[20:21] op_sel_hi:[1,0]
	v_pk_mul_f32 v[14:15], v[10:11], v[20:21] op_sel_hi:[1,0]
	v_pk_mul_f32 v[24:25], v[16:17], v[20:21] op_sel_hi:[1,0]
	v_pk_mul_f32 v[16:17], v[12:13], v[20:21] op_sel_hi:[1,0]
	s_and_b64 vcc, exec, s[4:5]
	v_cvt_pk_bf16_f32 v10, v22, v23
	v_cvt_pk_bf16_f32 v11, v24, v25
	v_cvt_pk_bf16_f32 v12, v14, v15
	v_cvt_pk_bf16_f32 v13, v16, v17
	s_cbranch_vccnz .LBB0_1297
	v_add_u32_e32 v14, s24, v164
	v_ashrrev_i32_e32 v15, 31, v14
	v_lshlrev_b64 v[14:15], 9, v[14:15]
	v_lshl_add_u64 v[14:15], v[148:149], 0, v[14:15]
	s_mov_b64 s[0:1], 0
	global_store_dwordx4 v[14:15], v[10:13], off
